# baseline (speedup 1.0000x reference)
; #define GRID_SYNC() do { asm volatile("s_waitcnt vmcnt(0) lgkmcnt(0)" ::: "memory"); grid.sync(); \
;     __builtin_amdgcn_fence(__ATOMIC_ACQUIRE, "agent"); } while (0)
; __global__ void __launch_bounds__(512, 2) mega(Params p_arg) {
;     ...
;   GRID_SYNC();
.LBB0_56:
	s_nop 0
	global_load_dword v2, v0, s[0:1] offset:32 sc1
	s_waitcnt vmcnt(0)
	v_and_b32_e32 v2, 0xffff0000, v2
	v_cmp_ne_u32_e32 vcc, v2, v1
	s_or_b64 s[4:5], vcc, s[4:5]
	s_andn2_b64 exec, exec, s[4:5]
	s_cbranch_execnz .LBB0_56

; __device__ __forceinline__ unsigned xb_ld(unsigned* p) { return __hip_atomic_load(p, __ATOMIC_RELAXED, __HIP_MEMORY_SCOPE_AGENT); }
; __device__ __forceinline__ unsigned xb_add(unsigned* p, unsigned v) { return __hip_atomic_fetch_add(p, v, __ATOMIC_RELAXED, __HIP_MEMORY_SCOPE_AGENT); }
; __device__ __forceinline__ unsigned xb_xcc_id() { return (unsigned)__builtin_amdgcn_s_getreg((3 << 11) | 20) & 0xFu; }
; #define XB_SPIN(cond, bar) do { unsigned _sp = 0; while (cond) { __builtin_amdgcn_s_sleep(1); \
;     if ((++_sp & 255u) == 0u) { if (xb_ld(&(bar)[XB_TMO])) break; if (_sp > XB_SPIN_CAP) { atomicAdd(&(bar)[XB_TMO], 1u); break; } } } } while (0)
;   if (tid == 0) {
;     const unsigned x = xb_xcc_id();
;     xb_add(&bar[XB_XCNT(x)], 1u);
;     __threadfence();
;     const unsigned old = xb_add(&bar[XB_CNT], 1u), gen = 0u;
;     if (old + 1u == (gen + 1u) * G) xb_add(&bar[XB_GEN], 1u); else XB_SPIN(xb_ld(&bar[XB_GEN]) == gen, bar);
.LBB0_68:
	s_and_b32 s10, s17, 0xff
	s_cmp_lg_u32 s10, 0
	s_mov_b64 s[12:13], -1
	s_nop 0
	s_cbranch_scc0 .LBB0_71
	s_mov_b64 s[14:15], -1
	s_and_b64 vcc, exec, s[12:13]
	s_cbranch_vccz .LBB0_67

; __device__ __forceinline__ unsigned xb_ld(unsigned* p) { return __hip_atomic_load(p, __ATOMIC_RELAXED, __HIP_MEMORY_SCOPE_AGENT); }
; __device__ __forceinline__ unsigned xb_add(unsigned* p, unsigned v) { return __hip_atomic_fetch_add(p, v, __ATOMIC_RELAXED, __HIP_MEMORY_SCOPE_AGENT); }
; #define XB_SPIN(cond, bar) do { unsigned _sp = 0; while (cond) { __builtin_amdgcn_s_sleep(1); \
;     if ((++_sp & 255u) == 0u) { if (xb_ld(&(bar)[XB_TMO])) break; if (_sp > XB_SPIN_CAP) { atomicAdd(&(bar)[XB_TMO], 1u); break; } } } } while (0)
; __device__ __forceinline__ void xcd_barrier(const XcdBarrier& b, int tid, const unsigned gen) {
;   asm volatile("s_waitcnt vmcnt(0)" ::: "memory");
;   __syncthreads();
;   if (tid == 0) {
;     unsigned* bar = b.bar;
;     __builtin_amdgcn_s_waitcnt(0);
;     const unsigned old = xb_add(&bar[XB_XSUB(b.x)], 1u);
;     if (old + 1u == (gen + 1u) * b.nloc) {
;       __builtin_amdgcn_fence(__ATOMIC_RELEASE, "agent");
;       asm volatile("s_waitcnt vmcnt(0)" ::: "memory");
;       const unsigned og = xb_add(&bar[XB_TOP], 1u);
;       const unsigned tg = gen;
;       if (og + 1u == (tg + 1u) * b.nx) xb_add(&bar[XB_TOPGEN], 1u);
;       else XB_SPIN(xb_ld(&bar[XB_TOPGEN]) == tg, bar);
;       __builtin_amdgcn_fence(__ATOMIC_ACQUIRE, "agent");
;       xb_add(&bar[XB_XGEN(b.x)], 1u);
;     } else {
;       XB_SPIN(xb_ld(&bar[XB_XGEN(b.x)]) == gen, bar);
;       __builtin_amdgcn_fence(__ATOMIC_ACQUIRE, "agent");
;     }
.LBB0_624:
	s_and_b32 s14, s18, 0xff
	s_mov_b64 s[12:13], -1
	s_cmp_lg_u32 s14, 0
	s_mov_b64 s[16:17], -1
	s_nop 0
	s_cbranch_scc1 .LBB0_627
	global_load_dword v1, v0, s[24:25] offset:512 sc1
	s_waitcnt vmcnt(0)
	v_cmp_eq_u32_e32 vcc, 0, v1
	s_cbranch_vccnz .LBB0_629
	s_mov_b64 s[16:17], 0
	s_mov_b64 s[14:15], -1

; __device__ __forceinline__ unsigned xb_ld(unsigned* p) { return __hip_atomic_load(p, __ATOMIC_RELAXED, __HIP_MEMORY_SCOPE_AGENT); }
; __device__ __forceinline__ unsigned xb_add(unsigned* p, unsigned v) { return __hip_atomic_fetch_add(p, v, __ATOMIC_RELAXED, __HIP_MEMORY_SCOPE_AGENT); }
; #define XB_SPIN(cond, bar) do { unsigned _sp = 0; while (cond) { __builtin_amdgcn_s_sleep(1); \
;     if ((++_sp & 255u) == 0u) { if (xb_ld(&(bar)[XB_TMO])) break; if (_sp > XB_SPIN_CAP) { atomicAdd(&(bar)[XB_TMO], 1u); break; } } } } while (0)
; __device__ __forceinline__ void xcd_barrier(const XcdBarrier& b, int tid, const unsigned gen) {
;   asm volatile("s_waitcnt vmcnt(0)" ::: "memory");
;   __syncthreads();
;   if (tid == 0) {
;     unsigned* bar = b.bar;
;     __builtin_amdgcn_s_waitcnt(0);
;     const unsigned old = xb_add(&bar[XB_XSUB(b.x)], 1u);
;     if (old + 1u == (gen + 1u) * b.nloc) {
;       __builtin_amdgcn_fence(__ATOMIC_RELEASE, "agent");
;       asm volatile("s_waitcnt vmcnt(0)" ::: "memory");
;       const unsigned og = xb_add(&bar[XB_TOP], 1u);
;       const unsigned tg = gen;
;       if (og + 1u == (tg + 1u) * b.nx) xb_add(&bar[XB_TOPGEN], 1u);
;       else XB_SPIN(xb_ld(&bar[XB_TOPGEN]) == tg, bar);
;       __builtin_amdgcn_fence(__ATOMIC_ACQUIRE, "agent");
;       xb_add(&bar[XB_XGEN(b.x)], 1u);
;     } else {
;       XB_SPIN(xb_ld(&bar[XB_XGEN(b.x)]) == gen, bar);
;       __builtin_amdgcn_fence(__ATOMIC_ACQUIRE, "agent");
;     }
.LBB0_641:
	s_and_b32 s14, s21, 0xff
	s_cmp_lg_u32 s14, 0
	s_mov_b64 s[16:17], -1
	s_nop 0
	s_cbranch_scc1 .LBB0_644
	global_load_dword v1, v0, s[6:7] sc1
	s_waitcnt vmcnt(0)
	v_cmp_eq_u32_e32 vcc, 0, v1
	s_cbranch_vccnz .LBB0_646
	s_mov_b64 s[16:17], 0
	s_mov_b64 s[14:15], -1
